# P5a tiles produced by the workgroup that consumes them in the gate phase; grid barrier between the two phases skipped (G=256)
# speedup vs baseline: 1.0704x; 1.0000x over previous
; #define PG8_STAGE(bufoff, gbase, voff) do { _Pragma("unroll") for (int _i = 0; _i < 2; ++_i) \
;         __builtin_amdgcn_global_load_lds((const unsigned*)((const char*)(gbase) + (voff)[_i]), (LAS unsigned*)(lds + (bufoff) + ldsw + _i * 8192), 16, 0, 0); } while (0)
; #define PG8_WAIT_V(n) asm volatile("s_waitcnt vmcnt(" #n ")" ::: "memory")
; #define PG8_BAR __builtin_amdgcn_s_barrier()
;     __device__ bool next(int i, Unit& u) const {
;         if (G == 256) {
;             const int k = i >> 2; if (k >= 2) return false;
;             const int r = c >> 3; u.pm = k * 64 + (c & 7) * 8 + (r >> 2); u.pn = (i & 3) * 4 + (r & 3); return true; }
;         const int su = (i >> 2) * G + c; if (su >= 512) return false;
;         u.pm = su >> 2; u.pn = (i & 3) * 4 + (su & 3); return true;
; template <class Epi, class Sched, bool ALIGN_EPI = false, bool SP2 = false>
; __device__ __forceinline__ void gemm_phase(LAS unsigned char* lds, const Gemm g, const Sched& S, const Epi& E) {
;     ...
;     const char* cA = (const char*)g.A + (size_t)cur.pm * tstep; const char* cB = (const char*)g.Bt + (size_t)cur.pn * tstep;
;     if constexpr (SP2) {
;         PG8_STAGE(PG8_SB(0, 0), cB, voffB); PG8_STAGE(PG8_SB(0, 1), cB + hstep, voffB); PG8_STAGE(PG8_SA(0, 0), cA, voffA); PG8_STAGE(PG8_SA(0, 1), cA + hstep, voffA);
;         if (wr == 1) PG8_BAR;
;         PG8_WAIT_V(2); PG8_BAR;
;         PG8_STAGE(PG8_SB(1, 0), cB + kstep, voffB); PG8_STAGE(PG8_SA(1, 0), cA + kstep, voffA); PG8_STAGE(PG8_SB(1, 1), cB + hstep + kstep, voffB);
;         PG8_WAIT_V(6); PG8_BAR;
;     } else {
;         PG8_STAGE(PG8_SB(0, 0), cB, voffB); PG8_STAGE(PG8_SA(0, 0), cA, voffA); PG8_STAGE(PG8_SB(0, 1), cB + hstep, voffB); PG8_STAGE(PG8_SA(0, 1), cA + hstep, voffA);
;         if (wr == 1) PG8_BAR;
;         PG8_WAIT_V(4); PG8_BAR;
;         PG8_STAGE(PG8_SB(1, 0), cB + kstep, voffB); PG8_STAGE(PG8_SA(1, 0), cA + kstep, voffA); PG8_STAGE(PG8_SB(1, 1), cB + hstep + kstep, voffB);
;         PG8_WAIT_V(6); PG8_BAR;
;     }
.LBB0_819:
	v_readlane_b32 s100, v254, 0
	v_readlane_b32 s101, v253, 39
	s_cmpk_lg_i32 s26, 0x100
	s_cbranch_scc1 .Lmy_p5a_map_keep
	s_and_b32 s100, s90, 7
	s_lshl_b32 s100, s100, 3
	s_lshr_b32 s101, s90, 5
	s_add_i32 s100, s100, s101
	s_bfe_u32 s101, s90, 0x20003
.Lmy_p5a_map_keep:
	v_mov_b32_e32 v7, v224
	s_and_b64 vcc, exec, s[96:97]
	v_readfirstlane_b32 s69, v7
	s_cbranch_vccnz .LBB0_809
	v_lshlrev_b32_e32 v1, 4, v7
	v_add_u32_e32 v0, 0x2000, v1
	v_ashrrev_i32_e32 v2, 31, v0
	v_lshrrev_b32_e32 v2, 22, v2
	v_add_u32_e32 v2, v0, v2
	v_ashrrev_i32_e32 v2, 10, v2
	v_mul_i32_i24_e32 v3, 0x400, v2
	v_sub_u32_e32 v0, v0, v3
	v_lshrrev_b32_e32 v3, 4, v0
	v_bitop3_b32 v0, v3, v0, 32 bitop3:0x6c
	v_ashrrev_i32_e32 v3, 31, v0
	v_lshrrev_b32_e32 v3, 26, v3
	v_add_u32_e32 v3, v0, v3
	v_ashrrev_i32_e32 v4, 6, v3
	v_lshlrev_b32_e32 v5, 3, v2
	v_and_b32_e32 v3, 0xc0, v3
	v_and_b32_e32 v5, -16, v5
	v_sub_u32_e32 v0, v0, v3
	v_bfe_i32 v3, v7, 27, 1
	v_add_u32_e32 v5, v4, v5
	v_lshrrev_b32_e32 v3, 22, v3
	v_and_b32_e32 v4, 3, v4
	s_mov_b32 s14, 0x7fffe0
	v_lshrrev_b32_e32 v6, 2, v5
	v_lshlrev_b32_e32 v8, 1, v5
	v_lshlrev_b32_e32 v2, 5, v2
	v_ashrrev_i16_sdwa v0, v216, sext(v0) dst_sel:DWORD dst_unused:UNUSED_PAD src0_sel:DWORD src1_sel:BYTE_0
	v_add_u32_e32 v3, v1, v3
	v_and_or_b32 v4, v5, s14, v4
	v_and_b32_e32 v6, 4, v6
	v_and_b32_e32 v8, 24, v8
	v_and_b32_e32 v2, 32, v2
	v_bfe_i32 v0, v0, 0, 16
	v_and_b32_e32 v3, 0xfffffc00, v3
	v_or3_b32 v4, v4, v6, v8
	v_add_lshl_u32 v2, v2, v0, 1
	v_sub_u32_e32 v1, v1, v3
	v_lshl_add_u32 v0, v4, 9, v2
	v_lshl_add_u32 v2, v5, 9, v2
	v_lshrrev_b32_e32 v3, 4, v1
	v_ashrrev_i32_e32 v5, 31, v7
	v_bitop3_b32 v1, v3, v1, 32 bitop3:0x6c
	v_lshrrev_b32_e32 v5, 26, v5
	v_ashrrev_i32_e32 v3, 31, v1
	v_add_u32_e32 v5, v7, v5
	v_lshrrev_b32_e32 v3, 26, v3
	v_ashrrev_i32_e32 v5, 6, v5
	s_lshl_b32 s4, s68, 19
	v_add_u32_e32 v3, v1, v3
	v_lshlrev_b32_e32 v6, 3, v5
	s_add_u32 s70, s36, s4
	v_ashrrev_i32_e32 v4, 6, v3
	v_and_b32_e32 v6, -16, v6
	v_and_b32_e32 v3, 0xc0, v3
	s_addc_u32 s71, s52, 0
	s_ashr_i32 s4, s69, 6
	v_add_u32_e32 v6, v4, v6
	v_and_b32_e32 v4, 3, v4
	v_sub_u32_e32 v1, v1, v3
	s_ashr_i32 s5, s69, 8
	s_lshl_b32 s72, s4, 10
	v_and_or_b32 v4, v6, s14, v4
	v_lshrrev_b32_e32 v8, 2, v6
	v_lshlrev_b32_e32 v9, 1, v6
	v_lshlrev_b32_e32 v5, 5, v5
	v_ashrrev_i16_sdwa v1, v216, sext(v1) dst_sel:DWORD dst_unused:UNUSED_PAD src0_sel:DWORD src1_sel:BYTE_0
	s_mul_i32 s14, s101, 0x20000
	v_and_b32_e32 v8, 4, v8
	v_and_b32_e32 v9, 24, v9
	v_and_b32_e32 v5, 32, v5
	v_bfe_i32 v1, v1, 0, 16
	s_mov_b32 s15, 0
	s_add_u32 s46, s70, s14
	v_or3_b32 v4, v4, v8, v9
	v_add_lshl_u32 v1, v5, v1, 1
	s_addc_u32 s47, s71, s15
	s_add_i32 s73, s72, 0
	v_lshl_add_u32 v64, v4, 9, v1
	s_add_i32 m0, s73, 0x10000
	s_mul_i32 s14, s100, 0x20000
	global_load_lds_dwordx4 v64, s[46:47]
	s_add_i32 m0, s73, 0x12000
	s_mov_b32 s15, 0
	s_add_u32 s44, s12, s14
	v_lshl_add_u32 v4, v6, 9, v1
	global_load_lds_dwordx4 v0, s[46:47]
	s_addc_u32 s45, s13, s15
	s_mov_b32 m0, s73
	s_add_i32 s74, s73, 0x2000
	global_load_lds_dwordx4 v4, s[44:45]
	s_mov_b32 m0, s74
	s_add_u32 s14, s46, 0x10000
	global_load_lds_dwordx4 v2, s[44:45]
	s_addc_u32 s15, s47, 0
	s_add_i32 m0, s73, 0x14000
	s_nop 0
	global_load_lds_dwordx4 v64, s[14:15]
	s_add_i32 m0, s73, 0x16000
	s_nop 0
	global_load_lds_dwordx4 v0, s[14:15]
	s_add_u32 s14, s44, 0x10000
	s_addc_u32 s15, s45, 0
	s_add_i32 s75, s73, 0x4000
	s_mov_b32 m0, s75
	s_add_i32 s76, s73, 0x6000
	global_load_lds_dwordx4 v4, s[14:15]
	s_mov_b32 m0, s76
	s_cmp_lg_u32 s5, 1
	global_load_lds_dwordx4 v2, s[14:15]
	s_cbranch_scc1 .LBB0_822
	s_barrier
.LBB0_822:
	s_lshl_b32 s14, s68, 11
	s_add_u32 s14, s53, s14
	v_lshrrev_b32_e32 v17, 1, v7
	v_lshl_add_u64 v[8:9], s[46:47], 0, v[64:65]
	v_mov_b32_e32 v1, v65
	s_addc_u32 s15, s67, 0
	v_and_b32_e32 v17, 24, v17
	s_lshl_b32 s4, s4, 5
	v_lshl_add_u64 v[10:11], s[46:47], 0, v[0:1]
	v_mov_b32_e32 v5, v65
	v_and_b32_e32 v16, 15, v7
	v_lshlrev_b32_e32 v18, 1, v17
	v_lshlrev_b32_e32 v7, 2, v7
	s_and_b32 s16, s4, 0x60
	s_add_i32 m0, s73, 0x18000
	v_lshl_add_u64 v[8:9], v[8:9], 0, s[34:35]
	v_lshl_add_u64 v[12:13], s[44:45], 0, v[4:5]
	v_mov_b32_e32 v3, v65
	v_lshl_or_b32 v6, s5, 6, v16
	v_lshl_or_b32 v16, v16, 6, v18
	s_lshl_b32 s5, s5, 13
	v_and_b32_e32 v7, 32, v7
	s_lshl_b32 s4, s16, 7
	s_waitcnt vmcnt(4)
	s_barrier
	global_load_lds_dwordx4 v[8:9], off
	v_lshl_add_u64 v[8:9], v[10:11], 0, s[34:35]
	s_add_i32 m0, s73, 0x1a000
	s_add_i32 s77, s73, 0x8000
	s_add_i32 s78, s73, 0xa000
	v_lshl_add_u64 v[14:15], s[44:45], 0, v[2:3]
	v_bitop3_b32 v18, v16, s5, v7 bitop3:0xde
	v_bitop3_b32 v7, v16, s4, v7 bitop3:0xde
	global_load_lds_dwordx4 v[8:9], off
	v_lshl_add_u64 v[8:9], v[12:13], 0, s[34:35]
	s_mov_b32 m0, s77
	s_add_u32 s4, s46, 0x10080
	global_load_lds_dwordx4 v[8:9], off
	v_lshl_add_u64 v[8:9], v[14:15], 0, s[34:35]
	s_mov_b32 m0, s78
	s_addc_u32 s5, s47, 0
	global_load_lds_dwordx4 v[8:9], off
	s_add_i32 m0, s73, 0x1c000
	v_lshl_add_u64 v[8:9], s[4:5], 0, v[64:65]
	global_load_lds_dwordx4 v[8:9], off
	v_lshl_add_u64 v[8:9], s[4:5], 0, v[0:1]
	s_add_i32 m0, s73, 0x1e000
	v_readlane_b32 s4, v254, 0
	global_load_lds_dwordx4 v[8:9], off
	s_waitcnt vmcnt(6)
	v_or_b32_e32 v8, s16, v17
	v_add_u32_e32 v9, 0, v18
	s_mov_b64 s[16:17], s[90:91]
	v_readlane_b32 s79, v254, 13
	s_mov_b32 s80, s101
	s_mov_b32 s81, s100
	s_barrier
	v_readlane_b32 s5, v254, 1
	s_branch .LBB0_825

;     __device__ bool next(int i, Unit& u) const {
;         if (G == 256) {
;             const int k = i >> 2; if (k >= 2) return false;
;             const int r = c >> 3; u.pm = k * 64 + (c & 7) * 8 + (r >> 2); u.pn = (i & 3) * 4 + (r & 3); return true; }
;         const int su = (i >> 2) * G + c; if (su >= 512) return false;
;         u.pm = su >> 2; u.pn = (i & 3) * 4 + (su & 3); return true;
; template <class Epi, class Sched, bool ALIGN_EPI = false, bool SP2 = false>
; __device__ __forceinline__ void gemm_phase(LAS unsigned char* lds, const Gemm g, const Sched& S, const Epi& E) {
;     ...
;         const bool has_next = S.next(ui + 1, nxt);
;         const char* nA = has_next ? (const char*)g.A + (size_t)nxt.pm * tstep : cA; const char* nB = has_next ? (const char*)g.Bt + (size_t)nxt.pn * tstep : cB;
.LBB0_824:
	s_cmpk_lg_i32 s26, 0x100
	s_cbranch_scc1 .Lmy_p5a_next_keep
	s_add_i32 s20, s100, 64
	s_mov_b32 s18, s101

; __device__ __forceinline__ unsigned xb_ld(unsigned* p)              { return __hip_atomic_load(p, __ATOMIC_RELAXED, __HIP_MEMORY_SCOPE_AGENT); }
; __device__ __forceinline__ unsigned xb_add(unsigned* p, unsigned v) { return __hip_atomic_fetch_add(p, v, __ATOMIC_RELAXED, __HIP_MEMORY_SCOPE_AGENT); }
; #define XB_SPIN(cond, bar) do { unsigned _sp = 0; while (cond) { __builtin_amdgcn_s_sleep(1); \
;     if ((++_sp & 255u) == 0u) { if (xb_ld(&(bar)[XB_TMO])) break; if (_sp > XB_SPIN_CAP) { atomicAdd(&(bar)[XB_TMO], 1u); break; } } } } while (0)
; __device__ __forceinline__ void xcd_barrier(const XcdBarrier& b) {
;     asm volatile("s_waitcnt vmcnt(0)" ::: "memory");
;     __syncthreads();
;     if (threadIdx.x == 0) {
;         unsigned* bar = b.bar;
;         __builtin_amdgcn_s_waitcnt(0);
;         unsigned nloc = b.st[0], nx = b.st[1];
;         if (nloc == 0u) { xcd_barrier_complete(bar, b.x, nloc, nx); b.st[0] = nloc; b.st[1] = nx; }
;         const unsigned old = xb_add(&bar[XB_XSUB(b.x)], 1u);
;         const unsigned gen = old / nloc;
;         if (old + 1u == (gen + 1u) * nloc) {
;             __builtin_amdgcn_fence(__ATOMIC_RELEASE, "agent");
;             asm volatile("s_waitcnt vmcnt(0)" ::: "memory");
;             const unsigned og = xb_add(&bar[XB_TOP], 1u);
;             const unsigned tg = og / nx;
;             if (og + 1u == (tg + 1u) * nx) xb_add(&bar[XB_TOPGEN], 1u);
;             else XB_SPIN(xb_ld(&bar[XB_TOPGEN]) == tg, bar);
;             __builtin_amdgcn_fence(__ATOMIC_ACQUIRE, "agent");
;             xb_add(&bar[XB_XGEN(b.x)], 1u);
;             asm volatile("s_waitcnt vmcnt(0)" ::: "memory");
;         } else {
;             XB_SPIN(xb_ld(&bar[XB_XGEN(b.x)]) == gen, bar);
;             __builtin_amdgcn_fence(__ATOMIC_ACQUIRE, "agent");
;             asm volatile("s_waitcnt vmcnt(0)" ::: "memory");
;         }
;     }
;     __syncthreads();
; }
.LBB0_832:
	s_waitcnt vmcnt(0)
	s_waitcnt vmcnt(0) lgkmcnt(0)
	s_barrier
	s_mov_b64 s[0:1], exec
	v_readlane_b32 s4, v251, 2
	v_readlane_b32 s5, v251, 3
	v_readlane_b32 s52, v254, 57
	v_readlane_b32 s38, v254, 18
	v_readlane_b32 s42, v254, 49
	v_readlane_b32 s44, v254, 51
	s_and_b64 s[4:5], s[0:1], s[4:5]
	v_readlane_b32 s53, v254, 58
	v_readlane_b32 s39, v254, 19
	v_readlane_b32 s43, v254, 50
	v_readlane_b32 s45, v254, 52
	s_mov_b32 s36, 0x3a800000
	s_cmpk_eq_i32 s26, 0x100
	s_cbranch_scc1 .LBB0_884
	s_mov_b64 exec, s[4:5]
	s_cbranch_execz .LBB0_884
	v_readlane_b32 s4, v254, 34
	s_waitcnt vmcnt(0) expcnt(0) lgkmcnt(0)
	s_nop 0
	v_mov_b32_e32 v0, s4
	ds_read_b32 v2, v0
	v_readlane_b32 s4, v254, 35
	s_waitcnt lgkmcnt(0)
	v_cmp_ne_u32_e32 vcc, 0, v2
	v_mov_b32_e32 v0, s4
	ds_read_b32 v0, v0
	s_cbranch_vccnz .LBB0_848
	s_mov_b32 s10, 1
	s_branch .LBB0_836

; __global__ void __launch_bounds__(NTHR, 2) fwd_megakernel(Params prm) {
;     extern __shared__ __attribute__((aligned(16))) unsigned char shm[];
	.amdhsa_kernel _Z14fwd_megakernel6Params
		.amdhsa_group_segment_fixed_size 0
		.amdhsa_private_segment_fixed_size 0
		.amdhsa_kernarg_size 520
		.amdhsa_user_sgpr_count 2
		.amdhsa_user_sgpr_dispatch_ptr 0
		.amdhsa_user_sgpr_queue_ptr 0
		.amdhsa_user_sgpr_kernarg_segment_ptr 1
		.amdhsa_user_sgpr_dispatch_id 0
		.amdhsa_user_sgpr_kernarg_preload_length 0
		.amdhsa_user_sgpr_kernarg_preload_offset 0
		.amdhsa_user_sgpr_private_segment_size 0
		.amdhsa_uses_dynamic_stack 0
		.amdhsa_enable_private_segment 0
		.amdhsa_system_sgpr_workgroup_id_x 1
		.amdhsa_system_sgpr_workgroup_id_y 0
		.amdhsa_system_sgpr_workgroup_id_z 0
		.amdhsa_system_sgpr_workgroup_info 0
		.amdhsa_system_vgpr_workitem_id 2
		.amdhsa_next_free_vgpr 256
		.amdhsa_next_free_sgpr 102
		.amdhsa_accum_offset 256
		.amdhsa_reserve_vcc 1
		.amdhsa_float_round_mode_32 0
		.amdhsa_float_round_mode_16_64 0
		.amdhsa_float_denorm_mode_32 3
		.amdhsa_float_denorm_mode_16_64 3
		.amdhsa_dx10_clamp 1
		.amdhsa_ieee_mode 1
		.amdhsa_fp16_overflow 0
		.amdhsa_tg_split 0
		.amdhsa_exception_fp_ieee_invalid_op 0
		.amdhsa_exception_fp_denorm_src 0
		.amdhsa_exception_fp_ieee_div_zero 0
		.amdhsa_exception_fp_ieee_overflow 0
		.amdhsa_exception_fp_ieee_underflow 0
		.amdhsa_exception_fp_ieee_inexact 0
		.amdhsa_exception_int_div_zero 0
	.end_amdhsa_kernel

; __global__ void __launch_bounds__(NTHR, 2) fwd_megakernel(Params prm) {
;     extern __shared__ __attribute__((aligned(16))) unsigned char shm[];
amdhsa.kernels:
  - .agpr_count:     0
    .args:
      - .offset:         0
        .size:           264
        .value_kind:     by_value
      - .offset:         264
        .size:           4
        .value_kind:     hidden_block_count_x
      - .offset:         268
        .size:           4
        .value_kind:     hidden_block_count_y
      - .offset:         272
        .size:           4
        .value_kind:     hidden_block_count_z
      - .offset:         276
        .size:           2
        .value_kind:     hidden_group_size_x
      - .offset:         278
        .size:           2
        .value_kind:     hidden_group_size_y
      - .offset:         280
        .size:           2
        .value_kind:     hidden_group_size_z
      - .offset:         282
        .size:           2
        .value_kind:     hidden_remainder_x
      - .offset:         284
        .size:           2
        .value_kind:     hidden_remainder_y
      - .offset:         286
        .size:           2
        .value_kind:     hidden_remainder_z
      - .offset:         304
        .size:           8
        .value_kind:     hidden_global_offset_x
      - .offset:         312
        .size:           8
        .value_kind:     hidden_global_offset_y
      - .offset:         320
        .size:           8
        .value_kind:     hidden_global_offset_z
      - .offset:         328
        .size:           2
        .value_kind:     hidden_grid_dims
      - .offset:         352
        .size:           8
        .value_kind:     hidden_multigrid_sync_arg
      - .offset:         384
        .size:           4
        .value_kind:     hidden_dynamic_lds_size
    .group_segment_fixed_size: 0
    .kernarg_segment_align: 8
    .kernarg_segment_size: 520
    .language:       OpenCL C
    .language_version:
      - 2
      - 0
    .max_flat_workgroup_size: 512
    .name:           _Z14fwd_megakernel6Params
    .private_segment_fixed_size: 0
    .sgpr_count:     108
    .sgpr_spill_count: 308
    .symbol:         _Z14fwd_megakernel6Params.kd
    .uniform_work_group_size: 1
    .uses_dynamic_stack: false
    .vgpr_count:     256
    .vgpr_spill_count: 0
    .wavefront_size: 64
